# 128x128 GEMM tail tiles: all A-fragment LDS reads issued up front with counted waits
# speedup vs baseline: 1.0264x; 1.0000x over previous
.LBB0_641:
	ds_read_b128 v[126:129], v99
	ds_read_b128 v[130:133], v101 offset:18432
	ds_read_b128 v[134:137], v101 offset:20736
	ds_read_b128 v[138:141], v101 offset:23040
	ds_read_b128 v[142:145], v101 offset:25344
	ds_read_b128 v[178:181], v99 offset:2304
	ds_read_b128 v[182:185], v99 offset:4608
	ds_read_b128 v[186:189], v99 offset:6912
	ds_read_b128 v[190:193], v99 offset:64
	ds_read_b128 v[194:197], v99 offset:2368
	ds_read_b128 v[198:201], v99 offset:4672
	ds_read_b128 v[202:205], v99 offset:6976
	s_add_i32 s21, s21, 64
	s_waitcnt lgkmcnt(10)
	v_mfma_f32_16x16x32_bf16 v[94:97], v[126:129], v[130:133], v[94:97]
	v_lshl_add_u64 v[106:107], v[106:107], 0, s[90:91]
	v_lshl_add_u64 v[108:109], v[108:109], 0, s[90:91]
	v_lshl_add_u64 v[110:111], v[110:111], 0, s[90:91]
	s_waitcnt lgkmcnt(9)
	v_mfma_f32_16x16x32_bf16 v[90:93], v[126:129], v[134:137], v[90:93]
	v_lshl_add_u64 v[112:113], v[112:113], 0, s[90:91]
	v_lshl_add_u64 v[114:115], v[114:115], 0, s[90:91]
	v_lshl_add_u64 v[116:117], v[116:117], 0, s[90:91]
	s_waitcnt lgkmcnt(8)
	v_mfma_f32_16x16x32_bf16 v[86:89], v[126:129], v[138:141], v[86:89]
	v_lshl_add_u64 v[118:119], v[118:119], 0, s[90:91]
	v_lshl_add_u64 v[120:121], v[120:121], 0, s[90:91]
	s_and_b64 vcc, exec, s[36:37]
	s_waitcnt lgkmcnt(7)
	v_mfma_f32_16x16x32_bf16 v[82:85], v[126:129], v[142:145], v[82:85]
	s_waitcnt lgkmcnt(6)
	v_mfma_f32_16x16x32_bf16 v[78:81], v[178:181], v[130:133], v[78:81]
	v_mfma_f32_16x16x32_bf16 v[46:49], v[178:181], v[134:137], v[46:49]
	v_mfma_f32_16x16x32_bf16 v[38:41], v[178:181], v[138:141], v[38:41]
	v_mfma_f32_16x16x32_bf16 v[30:33], v[178:181], v[142:145], v[30:33]
	s_waitcnt lgkmcnt(5)
	v_mfma_f32_16x16x32_bf16 v[34:37], v[182:185], v[130:133], v[34:37]
	v_mfma_f32_16x16x32_bf16 v[26:29], v[182:185], v[134:137], v[26:29]
	v_mfma_f32_16x16x32_bf16 v[18:21], v[182:185], v[138:141], v[18:21]
	v_mfma_f32_16x16x32_bf16 v[6:9], v[182:185], v[142:145], v[6:9]
	s_waitcnt lgkmcnt(4)
	v_mfma_f32_16x16x32_bf16 v[10:13], v[186:189], v[130:133], v[10:13]
	v_mfma_f32_16x16x32_bf16 v[22:25], v[186:189], v[134:137], v[22:25]
	ds_read_b128 v[134:137], v101 offset:20800
	v_mfma_f32_16x16x32_bf16 v[14:17], v[186:189], v[138:141], v[14:17]
	ds_read_b128 v[138:141], v101 offset:23104
	v_mfma_f32_16x16x32_bf16 v[2:5], v[186:189], v[142:145], v[2:5]
	ds_read_b128 v[126:129], v101 offset:18496
	ds_read_b128 v[142:145], v101 offset:25408
	s_waitcnt lgkmcnt(1)
	v_mfma_f32_16x16x32_bf16 v[94:97], v[190:193], v[126:129], v[94:97]
	v_mfma_f32_16x16x32_bf16 v[90:93], v[190:193], v[134:137], v[90:93]
	v_mfma_f32_16x16x32_bf16 v[86:89], v[190:193], v[138:141], v[86:89]
	s_waitcnt lgkmcnt(0)
	v_mfma_f32_16x16x32_bf16 v[82:85], v[190:193], v[142:145], v[82:85]
	v_mfma_f32_16x16x32_bf16 v[78:81], v[194:197], v[126:129], v[78:81]
	v_mfma_f32_16x16x32_bf16 v[46:49], v[194:197], v[134:137], v[46:49]
	v_mfma_f32_16x16x32_bf16 v[38:41], v[194:197], v[138:141], v[38:41]
	v_mfma_f32_16x16x32_bf16 v[30:33], v[194:197], v[142:145], v[30:33]
	v_mfma_f32_16x16x32_bf16 v[34:37], v[198:201], v[126:129], v[34:37]
	v_mfma_f32_16x16x32_bf16 v[26:29], v[198:201], v[134:137], v[26:29]
	v_mfma_f32_16x16x32_bf16 v[18:21], v[198:201], v[138:141], v[18:21]
	v_mfma_f32_16x16x32_bf16 v[6:9], v[198:201], v[142:145], v[6:9]
	v_mfma_f32_16x16x32_bf16 v[10:13], v[202:205], v[126:129], v[10:13]
	v_mfma_f32_16x16x32_bf16 v[22:25], v[202:205], v[134:137], v[22:25]
	v_mfma_f32_16x16x32_bf16 v[14:17], v[202:205], v[138:141], v[14:17]
	v_mfma_f32_16x16x32_bf16 v[2:5], v[202:205], v[142:145], v[2:5]
	s_waitcnt lgkmcnt(0)
	s_cbranch_vccnz .LBB0_645

.LBB0_1447:
	ds_read_b128 v[126:129], v99
	ds_read_b128 v[130:133], v101 offset:18432
	ds_read_b128 v[134:137], v101 offset:20736
	ds_read_b128 v[138:141], v101 offset:23040
	ds_read_b128 v[142:145], v101 offset:25344
	ds_read_b128 v[178:181], v99 offset:2304
	ds_read_b128 v[182:185], v99 offset:4608
	ds_read_b128 v[186:189], v99 offset:6912
	ds_read_b128 v[190:193], v99 offset:64
	ds_read_b128 v[194:197], v99 offset:2368
	ds_read_b128 v[198:201], v99 offset:4672
	ds_read_b128 v[202:205], v99 offset:6976
	s_add_i32 s20, s20, 64
	s_waitcnt lgkmcnt(10)
	v_mfma_f32_16x16x32_bf16 v[94:97], v[126:129], v[130:133], v[94:97]
	v_lshl_add_u64 v[106:107], v[106:107], 0, s[90:91]
	v_lshl_add_u64 v[108:109], v[108:109], 0, s[90:91]
	v_lshl_add_u64 v[110:111], v[110:111], 0, s[90:91]
	s_waitcnt lgkmcnt(9)
	v_mfma_f32_16x16x32_bf16 v[90:93], v[126:129], v[134:137], v[90:93]
	v_lshl_add_u64 v[112:113], v[112:113], 0, s[90:91]
	v_lshl_add_u64 v[114:115], v[114:115], 0, s[90:91]
	v_lshl_add_u64 v[116:117], v[116:117], 0, s[90:91]
	s_waitcnt lgkmcnt(8)
	v_mfma_f32_16x16x32_bf16 v[86:89], v[126:129], v[138:141], v[86:89]
	v_lshl_add_u64 v[118:119], v[118:119], 0, s[90:91]
	v_lshl_add_u64 v[120:121], v[120:121], 0, s[90:91]
	s_and_b64 vcc, exec, s[36:37]
	s_waitcnt lgkmcnt(7)
	v_mfma_f32_16x16x32_bf16 v[82:85], v[126:129], v[142:145], v[82:85]
	s_waitcnt lgkmcnt(6)
	v_mfma_f32_16x16x32_bf16 v[78:81], v[178:181], v[130:133], v[78:81]
	v_mfma_f32_16x16x32_bf16 v[42:45], v[178:181], v[134:137], v[42:45]
	v_mfma_f32_16x16x32_bf16 v[38:41], v[178:181], v[138:141], v[38:41]
	v_mfma_f32_16x16x32_bf16 v[30:33], v[178:181], v[142:145], v[30:33]
	s_waitcnt lgkmcnt(5)
	v_mfma_f32_16x16x32_bf16 v[34:37], v[182:185], v[130:133], v[34:37]
	v_mfma_f32_16x16x32_bf16 v[26:29], v[182:185], v[134:137], v[26:29]
	v_mfma_f32_16x16x32_bf16 v[18:21], v[182:185], v[138:141], v[18:21]
	v_mfma_f32_16x16x32_bf16 v[6:9], v[182:185], v[142:145], v[6:9]
	s_waitcnt lgkmcnt(4)
	v_mfma_f32_16x16x32_bf16 v[10:13], v[186:189], v[130:133], v[10:13]
	v_mfma_f32_16x16x32_bf16 v[22:25], v[186:189], v[134:137], v[22:25]
	ds_read_b128 v[134:137], v101 offset:20800
	v_mfma_f32_16x16x32_bf16 v[14:17], v[186:189], v[138:141], v[14:17]
	ds_read_b128 v[138:141], v101 offset:23104
	v_mfma_f32_16x16x32_bf16 v[2:5], v[186:189], v[142:145], v[2:5]
	ds_read_b128 v[126:129], v101 offset:18496
	ds_read_b128 v[142:145], v101 offset:25408
	s_waitcnt lgkmcnt(1)
	v_mfma_f32_16x16x32_bf16 v[94:97], v[190:193], v[126:129], v[94:97]
	v_mfma_f32_16x16x32_bf16 v[90:93], v[190:193], v[134:137], v[90:93]
	v_mfma_f32_16x16x32_bf16 v[86:89], v[190:193], v[138:141], v[86:89]
	s_waitcnt lgkmcnt(0)
	v_mfma_f32_16x16x32_bf16 v[82:85], v[190:193], v[142:145], v[82:85]
	v_mfma_f32_16x16x32_bf16 v[78:81], v[194:197], v[126:129], v[78:81]
	v_mfma_f32_16x16x32_bf16 v[42:45], v[194:197], v[134:137], v[42:45]
	v_mfma_f32_16x16x32_bf16 v[38:41], v[194:197], v[138:141], v[38:41]
	v_mfma_f32_16x16x32_bf16 v[30:33], v[194:197], v[142:145], v[30:33]
	v_mfma_f32_16x16x32_bf16 v[34:37], v[198:201], v[126:129], v[34:37]
	v_mfma_f32_16x16x32_bf16 v[26:29], v[198:201], v[134:137], v[26:29]
	v_mfma_f32_16x16x32_bf16 v[18:21], v[198:201], v[138:141], v[18:21]
	v_mfma_f32_16x16x32_bf16 v[6:9], v[198:201], v[142:145], v[6:9]
	v_mfma_f32_16x16x32_bf16 v[10:13], v[202:205], v[126:129], v[10:13]
	v_mfma_f32_16x16x32_bf16 v[22:25], v[202:205], v[134:137], v[22:25]
	v_mfma_f32_16x16x32_bf16 v[14:17], v[202:205], v[138:141], v[14:17]
	v_mfma_f32_16x16x32_bf16 v[2:5], v[202:205], v[142:145], v[2:5]
	s_waitcnt lgkmcnt(0)
	s_cbranch_vccnz .LBB0_1451

.LBB0_1778:
	ds_read_b128 v[126:129], v99
	ds_read_b128 v[130:133], v101 offset:18432
	ds_read_b128 v[134:137], v101 offset:20736
	ds_read_b128 v[138:141], v101 offset:23040
	ds_read_b128 v[142:145], v101 offset:25344
	ds_read_b128 v[178:181], v99 offset:2304
	ds_read_b128 v[182:185], v99 offset:4608
	ds_read_b128 v[186:189], v99 offset:6912
	ds_read_b128 v[190:193], v99 offset:64
	ds_read_b128 v[194:197], v99 offset:2368
	ds_read_b128 v[198:201], v99 offset:4672
	ds_read_b128 v[202:205], v99 offset:6976
	s_add_i32 s22, s22, 64
	s_waitcnt lgkmcnt(10)
	v_mfma_f32_16x16x32_bf16 v[94:97], v[126:129], v[130:133], v[94:97]
	v_lshl_add_u64 v[106:107], v[106:107], 0, s[90:91]
	v_lshl_add_u64 v[108:109], v[108:109], 0, s[90:91]
	v_lshl_add_u64 v[110:111], v[110:111], 0, s[90:91]
	s_waitcnt lgkmcnt(9)
	v_mfma_f32_16x16x32_bf16 v[90:93], v[126:129], v[134:137], v[90:93]
	v_lshl_add_u64 v[112:113], v[112:113], 0, s[90:91]
	v_lshl_add_u64 v[114:115], v[114:115], 0, s[90:91]
	v_lshl_add_u64 v[116:117], v[116:117], 0, s[90:91]
	s_waitcnt lgkmcnt(8)
	v_mfma_f32_16x16x32_bf16 v[86:89], v[126:129], v[138:141], v[86:89]
	v_lshl_add_u64 v[118:119], v[118:119], 0, s[90:91]
	v_lshl_add_u64 v[120:121], v[120:121], 0, s[90:91]
	s_and_b64 vcc, exec, s[0:1]
	s_waitcnt lgkmcnt(7)
	v_mfma_f32_16x16x32_bf16 v[82:85], v[126:129], v[142:145], v[82:85]
	s_waitcnt lgkmcnt(6)
	v_mfma_f32_16x16x32_bf16 v[70:73], v[178:181], v[130:133], v[70:73]
	v_mfma_f32_16x16x32_bf16 v[42:45], v[178:181], v[134:137], v[42:45]
	v_mfma_f32_16x16x32_bf16 v[38:41], v[178:181], v[138:141], v[38:41]
	v_mfma_f32_16x16x32_bf16 v[30:33], v[178:181], v[142:145], v[30:33]
	s_waitcnt lgkmcnt(5)
	v_mfma_f32_16x16x32_bf16 v[34:37], v[182:185], v[130:133], v[34:37]
	v_mfma_f32_16x16x32_bf16 v[26:29], v[182:185], v[134:137], v[26:29]
	v_mfma_f32_16x16x32_bf16 v[18:21], v[182:185], v[138:141], v[18:21]
	v_mfma_f32_16x16x32_bf16 v[6:9], v[182:185], v[142:145], v[6:9]
	s_waitcnt lgkmcnt(4)
	v_mfma_f32_16x16x32_bf16 v[10:13], v[186:189], v[130:133], v[10:13]
	v_mfma_f32_16x16x32_bf16 v[22:25], v[186:189], v[134:137], v[22:25]
	ds_read_b128 v[134:137], v101 offset:20800
	v_mfma_f32_16x16x32_bf16 v[14:17], v[186:189], v[138:141], v[14:17]
	ds_read_b128 v[138:141], v101 offset:23104
	v_mfma_f32_16x16x32_bf16 v[2:5], v[186:189], v[142:145], v[2:5]
	ds_read_b128 v[126:129], v101 offset:18496
	ds_read_b128 v[142:145], v101 offset:25408
	s_waitcnt lgkmcnt(1)
	v_mfma_f32_16x16x32_bf16 v[94:97], v[190:193], v[126:129], v[94:97]
	v_mfma_f32_16x16x32_bf16 v[90:93], v[190:193], v[134:137], v[90:93]
	v_mfma_f32_16x16x32_bf16 v[86:89], v[190:193], v[138:141], v[86:89]
	s_waitcnt lgkmcnt(0)
	v_mfma_f32_16x16x32_bf16 v[82:85], v[190:193], v[142:145], v[82:85]
	v_mfma_f32_16x16x32_bf16 v[70:73], v[194:197], v[126:129], v[70:73]
	v_mfma_f32_16x16x32_bf16 v[42:45], v[194:197], v[134:137], v[42:45]
	v_mfma_f32_16x16x32_bf16 v[38:41], v[194:197], v[138:141], v[38:41]
	v_mfma_f32_16x16x32_bf16 v[30:33], v[194:197], v[142:145], v[30:33]
	v_mfma_f32_16x16x32_bf16 v[34:37], v[198:201], v[126:129], v[34:37]
	v_mfma_f32_16x16x32_bf16 v[26:29], v[198:201], v[134:137], v[26:29]
	v_mfma_f32_16x16x32_bf16 v[18:21], v[198:201], v[138:141], v[18:21]
	v_mfma_f32_16x16x32_bf16 v[6:9], v[198:201], v[142:145], v[6:9]
	v_mfma_f32_16x16x32_bf16 v[10:13], v[202:205], v[126:129], v[10:13]
	v_mfma_f32_16x16x32_bf16 v[22:25], v[202:205], v[134:137], v[22:25]
	v_mfma_f32_16x16x32_bf16 v[14:17], v[202:205], v[138:141], v[14:17]
	v_mfma_f32_16x16x32_bf16 v[2:5], v[202:205], v[142:145], v[2:5]
	s_waitcnt lgkmcnt(0)
	s_cbranch_vccnz .LBB0_1782
